# phase C row statistics: coalesced loads (8 lanes per 128-byte line) + DPP partial-sum reduction
# baseline (speedup 1.0000x reference)
.LBB0_268:
	s_cmpk_gt_i32 s10, 0x2ff
	s_cselect_b64 s[2:3], -1, 0
	s_add_i32 s0, s10, 0xfffffd00
	s_cmpk_lt_i32 s10, 0x300
	s_cselect_b32 s4, 24, 32
	v_cvt_f32_ubyte0_e32 v0, s4
	v_rcp_iflag_f32_e32 v0, v0
	s_movk_i32 s11, 0x180
	s_cselect_b32 s5, s10, s0
	s_cselect_b32 s0, 0, 0x300
	v_mul_f32_e32 v0, 0x4f7ffffe, v0
	v_cvt_u32_f32_e32 v0, v0
	s_cselect_b32 s13, s11, 0x80
	s_sub_i32 s14, 0, s4
	s_abs_i32 s12, s5
	v_readfirstlane_b32 s15, v0
	s_mul_i32 s14, s14, s15
	s_mul_hi_u32 s14, s15, s14
	s_add_i32 s15, s15, s14
	s_mul_hi_u32 s14, s12, s15
	s_mul_i32 s15, s14, s4
	s_sub_i32 s12, s12, s15
	s_ashr_i32 s11, s5, 31
	s_add_i32 s15, s14, 1
	s_sub_i32 s16, s12, s4
	s_cmp_ge_u32 s12, s4
	s_cselect_b32 s14, s15, s14
	s_cselect_b32 s12, s16, s12
	s_add_i32 s15, s14, 1
	s_cmp_ge_u32 s12, s4
	s_cselect_b32 s12, s15, s14
	s_xor_b32 s12, s12, s11
	s_sub_i32 s11, s12, s11
	s_mul_i32 s4, s11, s4
	s_sub_i32 s4, s5, s4
	s_bfe_i32 s5, s4, 0x80000
	s_bfe_u32 s5, s5, 0x2000d
	s_add_i32 s5, s4, s5
	s_bfe_i32 s12, s5, 0x80000
	s_and_b32 s5, s5, 0xfc
	s_sub_i32 s4, s4, s5
	s_sext_i32_i8 s4, s4
	s_lshl_b32 s5, s11, 10
	s_lshl_b32 s11, s4, 8
	s_add_i32 s11, s11, s5
	v_ashrrev_i32_e32 v2, 1, v42
	v_add_u32_e32 v4, s11, v2
	v_mov_b64_e32 v[0:1], s[88:89]
	v_mad_i64_i32 v[0:1], s[4:5], v4, s84, v[0:1]
	v_and_b32_e32 v3, 1, v42
	v_lshl_add_u64 v[0:1], v[0:1], 0, s[0:1]
	v_and_b32_e32 v232, 0x1c0, v204
	v_lshrrev_b32_e32 v232, 1, v232
	v_bfe_u32 v233, v204, 3, 3
	v_lshl_or_b32 v232, v233, 2, v232
	v_add_u32_e32 v232, s11, v232
	v_mov_b64_e32 v[230:231], s[88:89]
	v_mad_i64_i32 v[230:231], vcc, v232, s84, v[230:231]
	v_lshl_add_u64 v[230:231], v[230:231], 0, s[0:1]
	v_and_b32_e32 v232, 7, v204
	v_lshlrev_b32_e32 v232, 4, v232
	v_mov_b32_e32 v233, v189
	v_lshl_add_u64 v[230:231], v[230:231], 0, v[232:233]
	s_movk_i32 vcc_lo, 0x1480
	s_mov_b32 vcc_hi, 0
	v_lshl_add_u64 v[232:233], v[230:231], 0, vcc
	s_lshr_b32 s0, s13, 1
	v_mul_u32_u24_e32 v4, s0, v3
	s_sext_i32_i16 s12, s12
	v_lshlrev_b32_e32 v188, 1, v4
	s_lshr_b32 s12, s12, 2
	v_lshl_add_u64 v[0:1], v[0:1], 0, v[188:189]
	s_lshr_b32 s0, s13, 4
	v_mov_b32_e32 v4, 0
	s_cmp_lt_u32 s0, 9
	s_cbranch_scc1 .Lcst_k128
	global_load_dwordx4 v[12:15], v[230:231], off
	global_load_dwordx4 v[16:19], v[230:231], off offset:128
	global_load_dwordx4 v[20:23], v[230:231], off offset:256
	global_load_dwordx4 v[24:27], v[230:231], off offset:384
	global_load_dwordx4 v[28:31], v[230:231], off offset:512
	global_load_dwordx4 v[32:35], v[230:231], off offset:640
	global_load_dwordx4 v[36:39], v[230:231], off offset:2624
	global_load_dwordx4 v[40:43], v[230:231], off offset:2752
	global_load_dwordx4 v[44:47], v[230:231], off offset:2880
	global_load_dwordx4 v[48:51], v[230:231], off offset:3008
	global_load_dwordx4 v[52:55], v[230:231], off offset:3136
	global_load_dwordx4 v[56:59], v[230:231], off offset:3264
	global_load_dwordx4 v[60:63], v[232:233], off
	global_load_dwordx4 v[64:67], v[232:233], off offset:128
	global_load_dwordx4 v[68:71], v[232:233], off offset:256
	global_load_dwordx4 v[72:75], v[232:233], off offset:384
	global_load_dwordx4 v[76:79], v[232:233], off offset:512
	global_load_dwordx4 v[80:83], v[232:233], off offset:640
	global_load_dwordx4 v[84:87], v[232:233], off offset:2624
	global_load_dwordx4 v[88:91], v[232:233], off offset:2752
	global_load_dwordx4 v[92:95], v[232:233], off offset:2880
	global_load_dwordx4 v[96:99], v[232:233], off offset:3008
	global_load_dwordx4 v[100:103], v[232:233], off offset:3136
	global_load_dwordx4 v[104:107], v[232:233], off offset:3264
	s_waitcnt vmcnt(0)
	v_mov_b32_e32 v4, 0
	v_lshlrev_b32_e32 v5, 16, v12
	v_lshlrev_b32_e32 v11, 16, v13
	v_and_b32_e32 v10, 0xffff0000, v12
	v_fmac_f32_e32 v4, v5, v5
	v_pk_mul_f32 v[10:11], v[10:11], v[10:11]
	v_and_b32_e32 v5, 0xffff0000, v13
	v_add_f32_e32 v4, v10, v4
	v_add_f32_e32 v6, v11, v4
	v_lshlrev_b32_e32 v4, 16, v14
	v_pk_mul_f32 v[4:5], v[4:5], v[4:5]
	s_nop 0
	v_add_f32_e32 v5, v5, v6
	v_add_f32_e32 v6, v4, v5
	v_lshlrev_b32_e32 v5, 16, v15
	v_and_b32_e32 v4, 0xffff0000, v14
	v_pk_mul_f32 v[4:5], v[4:5], v[4:5]
	s_nop 0
	v_add_f32_e32 v4, v4, v6
	v_add_f32_e32 v4, v5, v4
	v_and_b32_e32 v5, 0xffff0000, v15
	v_fmac_f32_e32 v4, v5, v5
	v_lshlrev_b32_e32 v5, 16, v16
	v_lshlrev_b32_e32 v11, 16, v17
	v_and_b32_e32 v10, 0xffff0000, v16
	v_fmac_f32_e32 v4, v5, v5
	v_pk_mul_f32 v[10:11], v[10:11], v[10:11]
	v_and_b32_e32 v5, 0xffff0000, v17
	v_add_f32_e32 v4, v10, v4
	v_add_f32_e32 v6, v11, v4
	v_lshlrev_b32_e32 v4, 16, v18
	v_pk_mul_f32 v[4:5], v[4:5], v[4:5]
	s_nop 0
	v_add_f32_e32 v5, v5, v6
	v_add_f32_e32 v6, v4, v5
	v_lshlrev_b32_e32 v5, 16, v19
	v_and_b32_e32 v4, 0xffff0000, v18
	v_pk_mul_f32 v[4:5], v[4:5], v[4:5]
	s_nop 0
	v_add_f32_e32 v4, v4, v6
	v_add_f32_e32 v4, v5, v4
	v_and_b32_e32 v5, 0xffff0000, v19
	v_fmac_f32_e32 v4, v5, v5
	v_lshlrev_b32_e32 v5, 16, v20
	v_lshlrev_b32_e32 v11, 16, v21
	v_and_b32_e32 v10, 0xffff0000, v20
	v_fmac_f32_e32 v4, v5, v5
	v_pk_mul_f32 v[10:11], v[10:11], v[10:11]
	v_and_b32_e32 v5, 0xffff0000, v21
	v_add_f32_e32 v4, v10, v4
	v_add_f32_e32 v6, v11, v4
	v_lshlrev_b32_e32 v4, 16, v22
	v_pk_mul_f32 v[4:5], v[4:5], v[4:5]
	s_nop 0
	v_add_f32_e32 v5, v5, v6
	v_add_f32_e32 v6, v4, v5
	v_lshlrev_b32_e32 v5, 16, v23
	v_and_b32_e32 v4, 0xffff0000, v22
	v_pk_mul_f32 v[4:5], v[4:5], v[4:5]
	s_nop 0
	v_add_f32_e32 v4, v4, v6
	v_add_f32_e32 v4, v5, v4
	v_and_b32_e32 v5, 0xffff0000, v23
	v_fmac_f32_e32 v4, v5, v5
	v_mov_b32_e32 v234, v4
	v_mov_b32_e32 v4, 0
	v_lshlrev_b32_e32 v5, 16, v24
	v_lshlrev_b32_e32 v11, 16, v25
	v_and_b32_e32 v10, 0xffff0000, v24
	v_fmac_f32_e32 v4, v5, v5
	v_pk_mul_f32 v[10:11], v[10:11], v[10:11]
	v_and_b32_e32 v5, 0xffff0000, v25
	v_add_f32_e32 v4, v10, v4
	v_add_f32_e32 v6, v11, v4
	v_lshlrev_b32_e32 v4, 16, v26
	v_pk_mul_f32 v[4:5], v[4:5], v[4:5]
	s_nop 0
	v_add_f32_e32 v5, v5, v6
	v_add_f32_e32 v6, v4, v5
	v_lshlrev_b32_e32 v5, 16, v27
	v_and_b32_e32 v4, 0xffff0000, v26
	v_pk_mul_f32 v[4:5], v[4:5], v[4:5]
	s_nop 0
	v_add_f32_e32 v4, v4, v6
	v_add_f32_e32 v4, v5, v4
	v_and_b32_e32 v5, 0xffff0000, v27
	v_fmac_f32_e32 v4, v5, v5
	v_lshlrev_b32_e32 v5, 16, v28
	v_lshlrev_b32_e32 v11, 16, v29
	v_and_b32_e32 v10, 0xffff0000, v28
	v_fmac_f32_e32 v4, v5, v5
	v_pk_mul_f32 v[10:11], v[10:11], v[10:11]
	v_and_b32_e32 v5, 0xffff0000, v29
	v_add_f32_e32 v4, v10, v4
	v_add_f32_e32 v6, v11, v4
	v_lshlrev_b32_e32 v4, 16, v30
	v_pk_mul_f32 v[4:5], v[4:5], v[4:5]
	s_nop 0
	v_add_f32_e32 v5, v5, v6
	v_add_f32_e32 v6, v4, v5
	v_lshlrev_b32_e32 v5, 16, v31
	v_and_b32_e32 v4, 0xffff0000, v30
	v_pk_mul_f32 v[4:5], v[4:5], v[4:5]
	s_nop 0
	v_add_f32_e32 v4, v4, v6
	v_add_f32_e32 v4, v5, v4
	v_and_b32_e32 v5, 0xffff0000, v31
	v_fmac_f32_e32 v4, v5, v5
	v_lshlrev_b32_e32 v5, 16, v32
	v_lshlrev_b32_e32 v11, 16, v33
	v_and_b32_e32 v10, 0xffff0000, v32
	v_fmac_f32_e32 v4, v5, v5
	v_pk_mul_f32 v[10:11], v[10:11], v[10:11]
	v_and_b32_e32 v5, 0xffff0000, v33
	v_add_f32_e32 v4, v10, v4
	v_add_f32_e32 v6, v11, v4
	v_lshlrev_b32_e32 v4, 16, v34
	v_pk_mul_f32 v[4:5], v[4:5], v[4:5]
	s_nop 0
	v_add_f32_e32 v5, v5, v6
	v_add_f32_e32 v6, v4, v5
	v_lshlrev_b32_e32 v5, 16, v35
	v_and_b32_e32 v4, 0xffff0000, v34
	v_pk_mul_f32 v[4:5], v[4:5], v[4:5]
	s_nop 0
	v_add_f32_e32 v4, v4, v6
	v_add_f32_e32 v4, v5, v4
	v_and_b32_e32 v5, 0xffff0000, v35
	v_fmac_f32_e32 v4, v5, v5
	v_mov_b32_e32 v235, v4
	v_mov_b32_e32 v4, 0
	v_lshlrev_b32_e32 v5, 16, v36
	v_lshlrev_b32_e32 v11, 16, v37
	v_and_b32_e32 v10, 0xffff0000, v36
	v_fmac_f32_e32 v4, v5, v5
	v_pk_mul_f32 v[10:11], v[10:11], v[10:11]
	v_and_b32_e32 v5, 0xffff0000, v37
	v_add_f32_e32 v4, v10, v4
	v_add_f32_e32 v6, v11, v4
	v_lshlrev_b32_e32 v4, 16, v38
	v_pk_mul_f32 v[4:5], v[4:5], v[4:5]
	s_nop 0
	v_add_f32_e32 v5, v5, v6
	v_add_f32_e32 v6, v4, v5
	v_lshlrev_b32_e32 v5, 16, v39
	v_and_b32_e32 v4, 0xffff0000, v38
	v_pk_mul_f32 v[4:5], v[4:5], v[4:5]
	s_nop 0
	v_add_f32_e32 v4, v4, v6
	v_add_f32_e32 v4, v5, v4
	v_and_b32_e32 v5, 0xffff0000, v39
	v_fmac_f32_e32 v4, v5, v5
	v_lshlrev_b32_e32 v5, 16, v40
	v_lshlrev_b32_e32 v11, 16, v41
	v_and_b32_e32 v10, 0xffff0000, v40
	v_fmac_f32_e32 v4, v5, v5
	v_pk_mul_f32 v[10:11], v[10:11], v[10:11]
	v_and_b32_e32 v5, 0xffff0000, v41
	v_add_f32_e32 v4, v10, v4
	v_add_f32_e32 v6, v11, v4
	v_lshlrev_b32_e32 v4, 16, v42
	v_pk_mul_f32 v[4:5], v[4:5], v[4:5]
	s_nop 0
	v_add_f32_e32 v5, v5, v6
	v_add_f32_e32 v6, v4, v5
	v_lshlrev_b32_e32 v5, 16, v43
	v_and_b32_e32 v4, 0xffff0000, v42
	v_pk_mul_f32 v[4:5], v[4:5], v[4:5]
	s_nop 0
	v_add_f32_e32 v4, v4, v6
	v_add_f32_e32 v4, v5, v4
	v_and_b32_e32 v5, 0xffff0000, v43
	v_fmac_f32_e32 v4, v5, v5
	v_lshlrev_b32_e32 v5, 16, v44
	v_lshlrev_b32_e32 v11, 16, v45
	v_and_b32_e32 v10, 0xffff0000, v44
	v_fmac_f32_e32 v4, v5, v5
	v_pk_mul_f32 v[10:11], v[10:11], v[10:11]
	v_and_b32_e32 v5, 0xffff0000, v45
	v_add_f32_e32 v4, v10, v4
	v_add_f32_e32 v6, v11, v4
	v_lshlrev_b32_e32 v4, 16, v46
	v_pk_mul_f32 v[4:5], v[4:5], v[4:5]
	s_nop 0
	v_add_f32_e32 v5, v5, v6
	v_add_f32_e32 v6, v4, v5
	v_lshlrev_b32_e32 v5, 16, v47
	v_and_b32_e32 v4, 0xffff0000, v46
	v_pk_mul_f32 v[4:5], v[4:5], v[4:5]
	s_nop 0
	v_add_f32_e32 v4, v4, v6
	v_add_f32_e32 v4, v5, v4
	v_and_b32_e32 v5, 0xffff0000, v47
	v_fmac_f32_e32 v4, v5, v5
	v_mov_b32_e32 v236, v4
	v_mov_b32_e32 v4, 0
	v_lshlrev_b32_e32 v5, 16, v48
	v_lshlrev_b32_e32 v11, 16, v49
	v_and_b32_e32 v10, 0xffff0000, v48
	v_fmac_f32_e32 v4, v5, v5
	v_pk_mul_f32 v[10:11], v[10:11], v[10:11]
	v_and_b32_e32 v5, 0xffff0000, v49
	v_add_f32_e32 v4, v10, v4
	v_add_f32_e32 v6, v11, v4
	v_lshlrev_b32_e32 v4, 16, v50
	v_pk_mul_f32 v[4:5], v[4:5], v[4:5]
	s_nop 0
	v_add_f32_e32 v5, v5, v6
	v_add_f32_e32 v6, v4, v5
	v_lshlrev_b32_e32 v5, 16, v51
	v_and_b32_e32 v4, 0xffff0000, v50
	v_pk_mul_f32 v[4:5], v[4:5], v[4:5]
	s_nop 0
	v_add_f32_e32 v4, v4, v6
	v_add_f32_e32 v4, v5, v4
	v_and_b32_e32 v5, 0xffff0000, v51
	v_fmac_f32_e32 v4, v5, v5
	v_lshlrev_b32_e32 v5, 16, v52
	v_lshlrev_b32_e32 v11, 16, v53
	v_and_b32_e32 v10, 0xffff0000, v52
	v_fmac_f32_e32 v4, v5, v5
	v_pk_mul_f32 v[10:11], v[10:11], v[10:11]
	v_and_b32_e32 v5, 0xffff0000, v53
	v_add_f32_e32 v4, v10, v4
	v_add_f32_e32 v6, v11, v4
	v_lshlrev_b32_e32 v4, 16, v54
	v_pk_mul_f32 v[4:5], v[4:5], v[4:5]
	s_nop 0
	v_add_f32_e32 v5, v5, v6
	v_add_f32_e32 v6, v4, v5
	v_lshlrev_b32_e32 v5, 16, v55
	v_and_b32_e32 v4, 0xffff0000, v54
	v_pk_mul_f32 v[4:5], v[4:5], v[4:5]
	s_nop 0
	v_add_f32_e32 v4, v4, v6
	v_add_f32_e32 v4, v5, v4
	v_and_b32_e32 v5, 0xffff0000, v55
	v_fmac_f32_e32 v4, v5, v5
	v_lshlrev_b32_e32 v5, 16, v56
	v_lshlrev_b32_e32 v11, 16, v57
	v_and_b32_e32 v10, 0xffff0000, v56
	v_fmac_f32_e32 v4, v5, v5
	v_pk_mul_f32 v[10:11], v[10:11], v[10:11]
	v_and_b32_e32 v5, 0xffff0000, v57
	v_add_f32_e32 v4, v10, v4
	v_add_f32_e32 v6, v11, v4
	v_lshlrev_b32_e32 v4, 16, v58
	v_pk_mul_f32 v[4:5], v[4:5], v[4:5]
	s_nop 0
	v_add_f32_e32 v5, v5, v6
	v_add_f32_e32 v6, v4, v5
	v_lshlrev_b32_e32 v5, 16, v59
	v_and_b32_e32 v4, 0xffff0000, v58
	v_pk_mul_f32 v[4:5], v[4:5], v[4:5]
	s_nop 0
	v_add_f32_e32 v4, v4, v6
	v_add_f32_e32 v4, v5, v4
	v_and_b32_e32 v5, 0xffff0000, v59
	v_fmac_f32_e32 v4, v5, v5
	v_mov_b32_e32 v237, v4
	v_mov_b32_e32 v4, 0
	v_lshlrev_b32_e32 v5, 16, v60
	v_lshlrev_b32_e32 v11, 16, v61
	v_and_b32_e32 v10, 0xffff0000, v60
	v_fmac_f32_e32 v4, v5, v5
	v_pk_mul_f32 v[10:11], v[10:11], v[10:11]
	v_and_b32_e32 v5, 0xffff0000, v61
	v_add_f32_e32 v4, v10, v4
	v_add_f32_e32 v6, v11, v4
	v_lshlrev_b32_e32 v4, 16, v62
	v_pk_mul_f32 v[4:5], v[4:5], v[4:5]
	s_nop 0
	v_add_f32_e32 v5, v5, v6
	v_add_f32_e32 v6, v4, v5
	v_lshlrev_b32_e32 v5, 16, v63
	v_and_b32_e32 v4, 0xffff0000, v62
	v_pk_mul_f32 v[4:5], v[4:5], v[4:5]
	s_nop 0
	v_add_f32_e32 v4, v4, v6
	v_add_f32_e32 v4, v5, v4
	v_and_b32_e32 v5, 0xffff0000, v63
	v_fmac_f32_e32 v4, v5, v5
	v_lshlrev_b32_e32 v5, 16, v64
	v_lshlrev_b32_e32 v11, 16, v65
	v_and_b32_e32 v10, 0xffff0000, v64
	v_fmac_f32_e32 v4, v5, v5
	v_pk_mul_f32 v[10:11], v[10:11], v[10:11]
	v_and_b32_e32 v5, 0xffff0000, v65
	v_add_f32_e32 v4, v10, v4
	v_add_f32_e32 v6, v11, v4
	v_lshlrev_b32_e32 v4, 16, v66
	v_pk_mul_f32 v[4:5], v[4:5], v[4:5]
	s_nop 0
	v_add_f32_e32 v5, v5, v6
	v_add_f32_e32 v6, v4, v5
	v_lshlrev_b32_e32 v5, 16, v67
	v_and_b32_e32 v4, 0xffff0000, v66
	v_pk_mul_f32 v[4:5], v[4:5], v[4:5]
	s_nop 0
	v_add_f32_e32 v4, v4, v6
	v_add_f32_e32 v4, v5, v4
	v_and_b32_e32 v5, 0xffff0000, v67
	v_fmac_f32_e32 v4, v5, v5
	v_lshlrev_b32_e32 v5, 16, v68
	v_lshlrev_b32_e32 v11, 16, v69
	v_and_b32_e32 v10, 0xffff0000, v68
	v_fmac_f32_e32 v4, v5, v5
	v_pk_mul_f32 v[10:11], v[10:11], v[10:11]
	v_and_b32_e32 v5, 0xffff0000, v69
	v_add_f32_e32 v4, v10, v4
	v_add_f32_e32 v6, v11, v4
	v_lshlrev_b32_e32 v4, 16, v70
	v_pk_mul_f32 v[4:5], v[4:5], v[4:5]
	s_nop 0
	v_add_f32_e32 v5, v5, v6
	v_add_f32_e32 v6, v4, v5
	v_lshlrev_b32_e32 v5, 16, v71
	v_and_b32_e32 v4, 0xffff0000, v70
	v_pk_mul_f32 v[4:5], v[4:5], v[4:5]
	s_nop 0
	v_add_f32_e32 v4, v4, v6
	v_add_f32_e32 v4, v5, v4
	v_and_b32_e32 v5, 0xffff0000, v71
	v_fmac_f32_e32 v4, v5, v5
	v_mov_b32_e32 v238, v4
	v_mov_b32_e32 v4, 0
	v_lshlrev_b32_e32 v5, 16, v72
	v_lshlrev_b32_e32 v11, 16, v73
	v_and_b32_e32 v10, 0xffff0000, v72
	v_fmac_f32_e32 v4, v5, v5
	v_pk_mul_f32 v[10:11], v[10:11], v[10:11]
	v_and_b32_e32 v5, 0xffff0000, v73
	v_add_f32_e32 v4, v10, v4
	v_add_f32_e32 v6, v11, v4
	v_lshlrev_b32_e32 v4, 16, v74
	v_pk_mul_f32 v[4:5], v[4:5], v[4:5]
	s_nop 0
	v_add_f32_e32 v5, v5, v6
	v_add_f32_e32 v6, v4, v5
	v_lshlrev_b32_e32 v5, 16, v75
	v_and_b32_e32 v4, 0xffff0000, v74
	v_pk_mul_f32 v[4:5], v[4:5], v[4:5]
	s_nop 0
	v_add_f32_e32 v4, v4, v6
	v_add_f32_e32 v4, v5, v4
	v_and_b32_e32 v5, 0xffff0000, v75
	v_fmac_f32_e32 v4, v5, v5
	v_lshlrev_b32_e32 v5, 16, v76
	v_lshlrev_b32_e32 v11, 16, v77
	v_and_b32_e32 v10, 0xffff0000, v76
	v_fmac_f32_e32 v4, v5, v5
	v_pk_mul_f32 v[10:11], v[10:11], v[10:11]
	v_and_b32_e32 v5, 0xffff0000, v77
	v_add_f32_e32 v4, v10, v4
	v_add_f32_e32 v6, v11, v4
	v_lshlrev_b32_e32 v4, 16, v78
	v_pk_mul_f32 v[4:5], v[4:5], v[4:5]
	s_nop 0
	v_add_f32_e32 v5, v5, v6
	v_add_f32_e32 v6, v4, v5
	v_lshlrev_b32_e32 v5, 16, v79
	v_and_b32_e32 v4, 0xffff0000, v78
	v_pk_mul_f32 v[4:5], v[4:5], v[4:5]
	s_nop 0
	v_add_f32_e32 v4, v4, v6
	v_add_f32_e32 v4, v5, v4
	v_and_b32_e32 v5, 0xffff0000, v79
	v_fmac_f32_e32 v4, v5, v5
	v_lshlrev_b32_e32 v5, 16, v80
	v_lshlrev_b32_e32 v11, 16, v81
	v_and_b32_e32 v10, 0xffff0000, v80
	v_fmac_f32_e32 v4, v5, v5
	v_pk_mul_f32 v[10:11], v[10:11], v[10:11]
	v_and_b32_e32 v5, 0xffff0000, v81
	v_add_f32_e32 v4, v10, v4
	v_add_f32_e32 v6, v11, v4
	v_lshlrev_b32_e32 v4, 16, v82
	v_pk_mul_f32 v[4:5], v[4:5], v[4:5]
	s_nop 0
	v_add_f32_e32 v5, v5, v6
	v_add_f32_e32 v6, v4, v5
	v_lshlrev_b32_e32 v5, 16, v83
	v_and_b32_e32 v4, 0xffff0000, v82
	v_pk_mul_f32 v[4:5], v[4:5], v[4:5]
	s_nop 0
	v_add_f32_e32 v4, v4, v6
	v_add_f32_e32 v4, v5, v4
	v_and_b32_e32 v5, 0xffff0000, v83
	v_fmac_f32_e32 v4, v5, v5
	v_mov_b32_e32 v239, v4
	v_mov_b32_e32 v4, 0
	v_lshlrev_b32_e32 v5, 16, v84
	v_lshlrev_b32_e32 v11, 16, v85
	v_and_b32_e32 v10, 0xffff0000, v84
	v_fmac_f32_e32 v4, v5, v5
	v_pk_mul_f32 v[10:11], v[10:11], v[10:11]
	v_and_b32_e32 v5, 0xffff0000, v85
	v_add_f32_e32 v4, v10, v4
	v_add_f32_e32 v6, v11, v4
	v_lshlrev_b32_e32 v4, 16, v86
	v_pk_mul_f32 v[4:5], v[4:5], v[4:5]
	s_nop 0
	v_add_f32_e32 v5, v5, v6
	v_add_f32_e32 v6, v4, v5
	v_lshlrev_b32_e32 v5, 16, v87
	v_and_b32_e32 v4, 0xffff0000, v86
	v_pk_mul_f32 v[4:5], v[4:5], v[4:5]
	s_nop 0
	v_add_f32_e32 v4, v4, v6
	v_add_f32_e32 v4, v5, v4
	v_and_b32_e32 v5, 0xffff0000, v87
	v_fmac_f32_e32 v4, v5, v5
	v_lshlrev_b32_e32 v5, 16, v88
	v_lshlrev_b32_e32 v11, 16, v89
	v_and_b32_e32 v10, 0xffff0000, v88
	v_fmac_f32_e32 v4, v5, v5
	v_pk_mul_f32 v[10:11], v[10:11], v[10:11]
	v_and_b32_e32 v5, 0xffff0000, v89
	v_add_f32_e32 v4, v10, v4
	v_add_f32_e32 v6, v11, v4
	v_lshlrev_b32_e32 v4, 16, v90
	v_pk_mul_f32 v[4:5], v[4:5], v[4:5]
	s_nop 0
	v_add_f32_e32 v5, v5, v6
	v_add_f32_e32 v6, v4, v5
	v_lshlrev_b32_e32 v5, 16, v91
	v_and_b32_e32 v4, 0xffff0000, v90
	v_pk_mul_f32 v[4:5], v[4:5], v[4:5]
	s_nop 0
	v_add_f32_e32 v4, v4, v6
	v_add_f32_e32 v4, v5, v4
	v_and_b32_e32 v5, 0xffff0000, v91
	v_fmac_f32_e32 v4, v5, v5
	v_lshlrev_b32_e32 v5, 16, v92
	v_lshlrev_b32_e32 v11, 16, v93
	v_and_b32_e32 v10, 0xffff0000, v92
	v_fmac_f32_e32 v4, v5, v5
	v_pk_mul_f32 v[10:11], v[10:11], v[10:11]
	v_and_b32_e32 v5, 0xffff0000, v93
	v_add_f32_e32 v4, v10, v4
	v_add_f32_e32 v6, v11, v4
	v_lshlrev_b32_e32 v4, 16, v94
	v_pk_mul_f32 v[4:5], v[4:5], v[4:5]
	s_nop 0
	v_add_f32_e32 v5, v5, v6
	v_add_f32_e32 v6, v4, v5
	v_lshlrev_b32_e32 v5, 16, v95
	v_and_b32_e32 v4, 0xffff0000, v94
	v_pk_mul_f32 v[4:5], v[4:5], v[4:5]
	s_nop 0
	v_add_f32_e32 v4, v4, v6
	v_add_f32_e32 v4, v5, v4
	v_and_b32_e32 v5, 0xffff0000, v95
	v_fmac_f32_e32 v4, v5, v5
	v_mov_b32_e32 v240, v4
	v_mov_b32_e32 v4, 0
	v_lshlrev_b32_e32 v5, 16, v96
	v_lshlrev_b32_e32 v11, 16, v97
	v_and_b32_e32 v10, 0xffff0000, v96
	v_fmac_f32_e32 v4, v5, v5
	v_pk_mul_f32 v[10:11], v[10:11], v[10:11]
	v_and_b32_e32 v5, 0xffff0000, v97
	v_add_f32_e32 v4, v10, v4
	v_add_f32_e32 v6, v11, v4
	v_lshlrev_b32_e32 v4, 16, v98
	v_pk_mul_f32 v[4:5], v[4:5], v[4:5]
	s_nop 0
	v_add_f32_e32 v5, v5, v6
	v_add_f32_e32 v6, v4, v5
	v_lshlrev_b32_e32 v5, 16, v99
	v_and_b32_e32 v4, 0xffff0000, v98
	v_pk_mul_f32 v[4:5], v[4:5], v[4:5]
	s_nop 0
	v_add_f32_e32 v4, v4, v6
	v_add_f32_e32 v4, v5, v4
	v_and_b32_e32 v5, 0xffff0000, v99
	v_fmac_f32_e32 v4, v5, v5
	v_lshlrev_b32_e32 v5, 16, v100
	v_lshlrev_b32_e32 v11, 16, v101
	v_and_b32_e32 v10, 0xffff0000, v100
	v_fmac_f32_e32 v4, v5, v5
	v_pk_mul_f32 v[10:11], v[10:11], v[10:11]
	v_and_b32_e32 v5, 0xffff0000, v101
	v_add_f32_e32 v4, v10, v4
	v_add_f32_e32 v6, v11, v4
	v_lshlrev_b32_e32 v4, 16, v102
	v_pk_mul_f32 v[4:5], v[4:5], v[4:5]
	s_nop 0
	v_add_f32_e32 v5, v5, v6
	v_add_f32_e32 v6, v4, v5
	v_lshlrev_b32_e32 v5, 16, v103
	v_and_b32_e32 v4, 0xffff0000, v102
	v_pk_mul_f32 v[4:5], v[4:5], v[4:5]
	s_nop 0
	v_add_f32_e32 v4, v4, v6
	v_add_f32_e32 v4, v5, v4
	v_and_b32_e32 v5, 0xffff0000, v103
	v_fmac_f32_e32 v4, v5, v5
	v_lshlrev_b32_e32 v5, 16, v104
	v_lshlrev_b32_e32 v11, 16, v105
	v_and_b32_e32 v10, 0xffff0000, v104
	v_fmac_f32_e32 v4, v5, v5
	v_pk_mul_f32 v[10:11], v[10:11], v[10:11]
	v_and_b32_e32 v5, 0xffff0000, v105
	v_add_f32_e32 v4, v10, v4
	v_add_f32_e32 v6, v11, v4
	v_lshlrev_b32_e32 v4, 16, v106
	v_pk_mul_f32 v[4:5], v[4:5], v[4:5]
	s_nop 0
	v_add_f32_e32 v5, v5, v6
	v_add_f32_e32 v6, v4, v5
	v_lshlrev_b32_e32 v5, 16, v107
	v_and_b32_e32 v4, 0xffff0000, v106
	v_pk_mul_f32 v[4:5], v[4:5], v[4:5]
	s_nop 0
	v_add_f32_e32 v4, v4, v6
	v_add_f32_e32 v4, v5, v4
	v_and_b32_e32 v5, 0xffff0000, v107
	v_fmac_f32_e32 v4, v5, v5
	v_mov_b32_e32 v241, v4
	s_branch .Lcst_red
.Lcst_k128:
	global_load_dwordx4 v[12:15], v[230:231], off
	global_load_dwordx4 v[16:19], v[230:231], off offset:128
	global_load_dwordx4 v[20:23], v[230:231], off offset:2624
	global_load_dwordx4 v[24:27], v[230:231], off offset:2752
	global_load_dwordx4 v[28:31], v[232:233], off
	global_load_dwordx4 v[32:35], v[232:233], off offset:128
	global_load_dwordx4 v[36:39], v[232:233], off offset:2624
	global_load_dwordx4 v[40:43], v[232:233], off offset:2752
	s_waitcnt vmcnt(0)
	v_mov_b32_e32 v4, 0
	v_lshlrev_b32_e32 v5, 16, v12
	v_lshlrev_b32_e32 v11, 16, v13
	v_and_b32_e32 v10, 0xffff0000, v12
	v_fmac_f32_e32 v4, v5, v5
	v_pk_mul_f32 v[10:11], v[10:11], v[10:11]
	v_and_b32_e32 v5, 0xffff0000, v13
	v_add_f32_e32 v4, v10, v4
	v_add_f32_e32 v6, v11, v4
	v_lshlrev_b32_e32 v4, 16, v14
	v_pk_mul_f32 v[4:5], v[4:5], v[4:5]
	s_nop 0
	v_add_f32_e32 v5, v5, v6
	v_add_f32_e32 v6, v4, v5
	v_lshlrev_b32_e32 v5, 16, v15
	v_and_b32_e32 v4, 0xffff0000, v14
	v_pk_mul_f32 v[4:5], v[4:5], v[4:5]
	s_nop 0
	v_add_f32_e32 v4, v4, v6
	v_add_f32_e32 v4, v5, v4
	v_and_b32_e32 v5, 0xffff0000, v15
	v_fmac_f32_e32 v4, v5, v5
	v_mov_b32_e32 v234, v4
	v_mov_b32_e32 v4, 0
	v_lshlrev_b32_e32 v5, 16, v16
	v_lshlrev_b32_e32 v11, 16, v17
	v_and_b32_e32 v10, 0xffff0000, v16
	v_fmac_f32_e32 v4, v5, v5
	v_pk_mul_f32 v[10:11], v[10:11], v[10:11]
	v_and_b32_e32 v5, 0xffff0000, v17
	v_add_f32_e32 v4, v10, v4
	v_add_f32_e32 v6, v11, v4
	v_lshlrev_b32_e32 v4, 16, v18
	v_pk_mul_f32 v[4:5], v[4:5], v[4:5]
	s_nop 0
	v_add_f32_e32 v5, v5, v6
	v_add_f32_e32 v6, v4, v5
	v_lshlrev_b32_e32 v5, 16, v19
	v_and_b32_e32 v4, 0xffff0000, v18
	v_pk_mul_f32 v[4:5], v[4:5], v[4:5]
	s_nop 0
	v_add_f32_e32 v4, v4, v6
	v_add_f32_e32 v4, v5, v4
	v_and_b32_e32 v5, 0xffff0000, v19
	v_fmac_f32_e32 v4, v5, v5
	v_mov_b32_e32 v235, v4
	v_mov_b32_e32 v4, 0
	v_lshlrev_b32_e32 v5, 16, v20
	v_lshlrev_b32_e32 v11, 16, v21
	v_and_b32_e32 v10, 0xffff0000, v20
	v_fmac_f32_e32 v4, v5, v5
	v_pk_mul_f32 v[10:11], v[10:11], v[10:11]
	v_and_b32_e32 v5, 0xffff0000, v21
	v_add_f32_e32 v4, v10, v4
	v_add_f32_e32 v6, v11, v4
	v_lshlrev_b32_e32 v4, 16, v22
	v_pk_mul_f32 v[4:5], v[4:5], v[4:5]
	s_nop 0
	v_add_f32_e32 v5, v5, v6
	v_add_f32_e32 v6, v4, v5
	v_lshlrev_b32_e32 v5, 16, v23
	v_and_b32_e32 v4, 0xffff0000, v22
	v_pk_mul_f32 v[4:5], v[4:5], v[4:5]
	s_nop 0
	v_add_f32_e32 v4, v4, v6
	v_add_f32_e32 v4, v5, v4
	v_and_b32_e32 v5, 0xffff0000, v23
	v_fmac_f32_e32 v4, v5, v5
	v_mov_b32_e32 v236, v4
	v_mov_b32_e32 v4, 0
	v_lshlrev_b32_e32 v5, 16, v24
	v_lshlrev_b32_e32 v11, 16, v25
	v_and_b32_e32 v10, 0xffff0000, v24
	v_fmac_f32_e32 v4, v5, v5
	v_pk_mul_f32 v[10:11], v[10:11], v[10:11]
	v_and_b32_e32 v5, 0xffff0000, v25
	v_add_f32_e32 v4, v10, v4
	v_add_f32_e32 v6, v11, v4
	v_lshlrev_b32_e32 v4, 16, v26
	v_pk_mul_f32 v[4:5], v[4:5], v[4:5]
	s_nop 0
	v_add_f32_e32 v5, v5, v6
	v_add_f32_e32 v6, v4, v5
	v_lshlrev_b32_e32 v5, 16, v27
	v_and_b32_e32 v4, 0xffff0000, v26
	v_pk_mul_f32 v[4:5], v[4:5], v[4:5]
	s_nop 0
	v_add_f32_e32 v4, v4, v6
	v_add_f32_e32 v4, v5, v4
	v_and_b32_e32 v5, 0xffff0000, v27
	v_fmac_f32_e32 v4, v5, v5
	v_mov_b32_e32 v237, v4
	v_mov_b32_e32 v4, 0
	v_lshlrev_b32_e32 v5, 16, v28
	v_lshlrev_b32_e32 v11, 16, v29
	v_and_b32_e32 v10, 0xffff0000, v28
	v_fmac_f32_e32 v4, v5, v5
	v_pk_mul_f32 v[10:11], v[10:11], v[10:11]
	v_and_b32_e32 v5, 0xffff0000, v29
	v_add_f32_e32 v4, v10, v4
	v_add_f32_e32 v6, v11, v4
	v_lshlrev_b32_e32 v4, 16, v30
	v_pk_mul_f32 v[4:5], v[4:5], v[4:5]
	s_nop 0
	v_add_f32_e32 v5, v5, v6
	v_add_f32_e32 v6, v4, v5
	v_lshlrev_b32_e32 v5, 16, v31
	v_and_b32_e32 v4, 0xffff0000, v30
	v_pk_mul_f32 v[4:5], v[4:5], v[4:5]
	s_nop 0
	v_add_f32_e32 v4, v4, v6
	v_add_f32_e32 v4, v5, v4
	v_and_b32_e32 v5, 0xffff0000, v31
	v_fmac_f32_e32 v4, v5, v5
	v_mov_b32_e32 v238, v4
	v_mov_b32_e32 v4, 0
	v_lshlrev_b32_e32 v5, 16, v32
	v_lshlrev_b32_e32 v11, 16, v33
	v_and_b32_e32 v10, 0xffff0000, v32
	v_fmac_f32_e32 v4, v5, v5
	v_pk_mul_f32 v[10:11], v[10:11], v[10:11]
	v_and_b32_e32 v5, 0xffff0000, v33
	v_add_f32_e32 v4, v10, v4
	v_add_f32_e32 v6, v11, v4
	v_lshlrev_b32_e32 v4, 16, v34
	v_pk_mul_f32 v[4:5], v[4:5], v[4:5]
	s_nop 0
	v_add_f32_e32 v5, v5, v6
	v_add_f32_e32 v6, v4, v5
	v_lshlrev_b32_e32 v5, 16, v35
	v_and_b32_e32 v4, 0xffff0000, v34
	v_pk_mul_f32 v[4:5], v[4:5], v[4:5]
	s_nop 0
	v_add_f32_e32 v4, v4, v6
	v_add_f32_e32 v4, v5, v4
	v_and_b32_e32 v5, 0xffff0000, v35
	v_fmac_f32_e32 v4, v5, v5
	v_mov_b32_e32 v239, v4
	v_mov_b32_e32 v4, 0
	v_lshlrev_b32_e32 v5, 16, v36
	v_lshlrev_b32_e32 v11, 16, v37
	v_and_b32_e32 v10, 0xffff0000, v36
	v_fmac_f32_e32 v4, v5, v5
	v_pk_mul_f32 v[10:11], v[10:11], v[10:11]
	v_and_b32_e32 v5, 0xffff0000, v37
	v_add_f32_e32 v4, v10, v4
	v_add_f32_e32 v6, v11, v4
	v_lshlrev_b32_e32 v4, 16, v38
	v_pk_mul_f32 v[4:5], v[4:5], v[4:5]
	s_nop 0
	v_add_f32_e32 v5, v5, v6
	v_add_f32_e32 v6, v4, v5
	v_lshlrev_b32_e32 v5, 16, v39
	v_and_b32_e32 v4, 0xffff0000, v38
	v_pk_mul_f32 v[4:5], v[4:5], v[4:5]
	s_nop 0
	v_add_f32_e32 v4, v4, v6
	v_add_f32_e32 v4, v5, v4
	v_and_b32_e32 v5, 0xffff0000, v39
	v_fmac_f32_e32 v4, v5, v5
	v_mov_b32_e32 v240, v4
	v_mov_b32_e32 v4, 0
	v_lshlrev_b32_e32 v5, 16, v40
	v_lshlrev_b32_e32 v11, 16, v41
	v_and_b32_e32 v10, 0xffff0000, v40
	v_fmac_f32_e32 v4, v5, v5
	v_pk_mul_f32 v[10:11], v[10:11], v[10:11]
	v_and_b32_e32 v5, 0xffff0000, v41
	v_add_f32_e32 v4, v10, v4
	v_add_f32_e32 v6, v11, v4
	v_lshlrev_b32_e32 v4, 16, v42
	v_pk_mul_f32 v[4:5], v[4:5], v[4:5]
	s_nop 0
	v_add_f32_e32 v5, v5, v6
	v_add_f32_e32 v6, v4, v5
	v_lshlrev_b32_e32 v5, 16, v43
	v_and_b32_e32 v4, 0xffff0000, v42
	v_pk_mul_f32 v[4:5], v[4:5], v[4:5]
	s_nop 0
	v_add_f32_e32 v4, v4, v6
	v_add_f32_e32 v4, v5, v4
	v_and_b32_e32 v5, 0xffff0000, v43
	v_fmac_f32_e32 v4, v5, v5
	v_mov_b32_e32 v241, v4
.Lcst_red:
	v_add_f32_dpp v234, v234, v234 quad_perm:[1,0,3,2] row_mask:0xf bank_mask:0xf
	v_add_f32_dpp v235, v235, v235 quad_perm:[1,0,3,2] row_mask:0xf bank_mask:0xf
	v_add_f32_dpp v236, v236, v236 quad_perm:[1,0,3,2] row_mask:0xf bank_mask:0xf
	v_add_f32_dpp v237, v237, v237 quad_perm:[1,0,3,2] row_mask:0xf bank_mask:0xf
	v_add_f32_dpp v238, v238, v238 quad_perm:[1,0,3,2] row_mask:0xf bank_mask:0xf
	v_add_f32_dpp v239, v239, v239 quad_perm:[1,0,3,2] row_mask:0xf bank_mask:0xf
	v_add_f32_dpp v240, v240, v240 quad_perm:[1,0,3,2] row_mask:0xf bank_mask:0xf
	v_add_f32_dpp v241, v241, v241 quad_perm:[1,0,3,2] row_mask:0xf bank_mask:0xf
	s_nop 1
	v_add_f32_dpp v234, v234, v234 quad_perm:[2,3,0,1] row_mask:0xf bank_mask:0xf
	v_add_f32_dpp v235, v235, v235 quad_perm:[2,3,0,1] row_mask:0xf bank_mask:0xf
	v_add_f32_dpp v236, v236, v236 quad_perm:[2,3,0,1] row_mask:0xf bank_mask:0xf
	v_add_f32_dpp v237, v237, v237 quad_perm:[2,3,0,1] row_mask:0xf bank_mask:0xf
	v_add_f32_dpp v238, v238, v238 quad_perm:[2,3,0,1] row_mask:0xf bank_mask:0xf
	v_add_f32_dpp v239, v239, v239 quad_perm:[2,3,0,1] row_mask:0xf bank_mask:0xf
	v_add_f32_dpp v240, v240, v240 quad_perm:[2,3,0,1] row_mask:0xf bank_mask:0xf
	v_add_f32_dpp v241, v241, v241 quad_perm:[2,3,0,1] row_mask:0xf bank_mask:0xf
	s_nop 1
	v_add_f32_dpp v234, v234, v234 row_half_mirror row_mask:0xf bank_mask:0xf
	v_add_f32_dpp v235, v235, v235 row_half_mirror row_mask:0xf bank_mask:0xf
	v_add_f32_dpp v236, v236, v236 row_half_mirror row_mask:0xf bank_mask:0xf
	v_add_f32_dpp v237, v237, v237 row_half_mirror row_mask:0xf bank_mask:0xf
	v_add_f32_dpp v238, v238, v238 row_half_mirror row_mask:0xf bank_mask:0xf
	v_add_f32_dpp v239, v239, v239 row_half_mirror row_mask:0xf bank_mask:0xf
	v_add_f32_dpp v240, v240, v240 row_half_mirror row_mask:0xf bank_mask:0xf
	v_add_f32_dpp v241, v241, v241 row_half_mirror row_mask:0xf bank_mask:0xf
	s_nop 1
	v_and_b32_e32 v5, 7, v204
	v_mov_b32_e32 v4, v234
	v_cmp_eq_u32_e32 vcc, 1, v5
	s_nop 1
	v_cndmask_b32_e32 v4, v4, v235, vcc
	v_cmp_eq_u32_e32 vcc, 2, v5
	s_nop 1
	v_cndmask_b32_e32 v4, v4, v236, vcc
	v_cmp_eq_u32_e32 vcc, 3, v5
	s_nop 1
	v_cndmask_b32_e32 v4, v4, v237, vcc
	v_cmp_eq_u32_e32 vcc, 4, v5
	s_nop 1
	v_cndmask_b32_e32 v4, v4, v238, vcc
	v_cmp_eq_u32_e32 vcc, 5, v5
	s_nop 1
	v_cndmask_b32_e32 v4, v4, v239, vcc
	v_cmp_eq_u32_e32 vcc, 6, v5
	s_nop 1
	v_cndmask_b32_e32 v4, v4, v240, vcc
	v_cmp_eq_u32_e32 vcc, 7, v5
	s_nop 1
	v_cndmask_b32_e32 v4, v4, v241, vcc
